# lever 1: MoBA unit prologue counted waits (two compiler vmcnt(0) -> vmcnt(3)): block-gate compute now overlaps the K0/V0/K1 LDS-DMA flight
# speedup vs baseline: 1.0112x; 1.0112x over previous
;   #define DMA_K(t,slot) glds16(ksrc+(long)(TKT(t))*KVBLK*D,(unsigned)__builtin_amdgcn_readfirstlane(kdst+(slot)))
;   #define DMA_V(t,slot) glds16(vsrc+(long)(TKT(t))*KVBLK*D,(unsigned)__builtin_amdgcn_readfirstlane(vdst+(slot)))
; template<int THRL> __device__ __forceinline__ void attn_unit(int b,int h,int qb,const bf16*Q,const bf16*__restrict__ K,const bf16*__restrict__ V,bf16*O,char*shm,const float*KMg,const float*rel_bias,bool newhead,bf16x8 (&qr)[4],const bf16*Qnext){
;     ...
;   const bf16*Qw=Q+(rowbase+q0+wid*QBLK)*DM+h*D;
;   const bf16*Kh=K+(long)(b*NHEAD+h)*SEQ*D,*Vh=V+(long)(b*NHEAD+h)*SEQ*D;
;   const unsigned lds0=(unsigned)(uintptr_t)shm;
;   float*wsf=(float*)(shm+LDS_WS)+wid*64;
;   const bf16*ksrc=Kh+(long)lane*D+wid*8;
;   const bf16*vsrc=Vh+(long)(16*(wid&3)+(lane>>2))*D+(wid>>2)*32+(lane&3)*8;
;   const unsigned kdst=lds0+LDS_K+wid*1024, vdst=lds0+LDS_V+wid*1024;
;     ...
;   const int vb0=(int)(lds0+LDS_V)+((lane>>4)&1)*32+(lane&3)*8+(4*hi+((lane&15)>>2))*64;
;   const char*Kbase=shm+LDS_K; bf16x8 kf[8];
;   const lds_cptr shm3=(lds_cptr)shm; const lds_cptr kp0=shm3+LDS_K+hi*1024+r32*16; const lds_cptr vp0=shm3+LDS_V+((lane>>4)&1)*32+(lane&3)*8+(4*hi+((lane&15)>>2))*64;
;   const int NT=(q0+QB)/KVBLK;
;   DMA_K(0,0);DMA_V(0,0);DMA_K(1,SLOTB);
;   unsigned sel=0u;
;   if(qb>0){ float g[7];
.LBB0_447:
	s_bfe_u32 s20, s43, 0x30008
	s_lshl_b32 s5, s20, 8
	s_lshl_b64 s[6:7], s[6:7], 18
	v_readlane_b32 s8, v254, 18
	s_add_u32 s8, s8, s6
	v_readlane_b32 s9, v254, 19
	s_addc_u32 s9, s9, s7
	v_readlane_b32 s10, v254, 16
	s_add_u32 s6, s10, s6
	v_readlane_b32 s10, v254, 17
	v_lshlrev_b32_e32 v2, 7, v238
	v_mov_b32_e32 v3, v0
	s_addc_u32 s7, s10, s7
	v_lshl_add_u64 v[2:3], s[8:9], 0, v[2:3]
	s_lshl_b32 s8, s77, 3
	s_ashr_i32 s9, s8, 31
	v_lshl_add_u64 v[218:219], s[8:9], 1, v[2:3]
	s_lshl_b32 s8, s77, 4
	v_lshrrev_b32_e32 v1, 2, v238
	v_and_or_b32 v1, s8, 48, v1
	v_lshlrev_b32_e32 v2, 7, v1
	v_mov_b32_e32 v3, v0
	v_lshl_add_u64 v[2:3], s[6:7], 0, v[2:3]
	s_ashr_i32 s6, s42, 3
	s_andn2_b32 s6, s6, 31
	s_ashr_i32 s7, s6, 31
	s_lshl_b32 s24, s77, 10
	s_cmp_lg_u32 0, -1
	v_lshl_add_u64 v[2:3], s[6:7], 1, v[2:3]
	s_cselect_b32 s6, 0, 0
	s_add_i32 s33, s24, s6
	s_add_i32 s6, s5, 0x100
	s_lshr_b32 s28, s6, 6
	v_and_b32_e32 v240, 24, v239
	s_add_i32 s82, s28, -4
	s_mov_b32 s83, s59
	v_lshlrev_b32_e32 v4, 1, v240
	v_mov_b32_e32 v5, v0
	s_lshl_b64 s[6:7], s[82:83], 13
	v_lshl_add_u64 v[220:221], v[2:3], 0, v[4:5]
	v_lshl_add_u64 v[2:3], v[218:219], 0, s[6:7]
	s_mov_b32 s8, m0
	s_mov_b32 m0, s33
	s_nop 0
	global_load_lds_dwordx4 v[2:3], off
	s_mov_b32 m0, s8
	s_add_i32 s10, s33, 0x6000
	v_lshl_add_u64 v[2:3], v[220:221], 0, s[6:7]
	s_mov_b32 s6, m0
	s_mov_b32 m0, s10
	s_nop 0
	global_load_lds_dwordx4 v[2:3], off
	s_mov_b32 m0, s6
	s_add_i32 s58, s28, -3
	s_lshl_b64 s[6:7], s[58:59], 13
	v_lshl_add_u64 v[2:3], v[218:219], 0, s[6:7]
	s_add_i32 s6, s33, 0x2000
	s_mov_b32 s7, m0
	s_mov_b32 m0, s6
	s_nop 0
	global_load_lds_dwordx4 v[2:3], off
	s_mov_b32 m0, s7
	s_cmp_eq_u32 s20, 0
	s_cselect_b64 s[6:7], -1, 0
	s_cmp_lg_u32 s20, 0
	s_cselect_b64 s[8:9], -1, 0
	v_mov_b32_e32 v223, 0
	s_and_b64 vcc, exec, s[6:7]
	s_cbranch_vccnz .LBB0_464
; template<int THRL> __device__ __forceinline__ void attn_unit(int b,int h,int qb,const bf16*Q,const bf16*__restrict__ K,const bf16*__restrict__ V,bf16*O,char*shm,const float*KMg,const float*rel_bias,bool newhead,bf16x8 (&qr)[4],const bf16*Qnext){
;     ...
;   if(qb>0){ float g[7];
;     #pragma unroll
;     for(int n=0;n<7;++n){ float a=0.f;
;       if(n<qb){
;         #pragma unroll
;         for(int d0=0;d0<4;++d0){ const h16x8v qv=__builtin_bit_cast(h16x8v,qr[d0]);
;           #pragma unroll
;           for(int j=0;j<8;++j)a+=(float)qv[j]*kml[n*64+16*d0+8*hi+j]; } }
;       { auto rr=__builtin_amdgcn_permlane32_swap(__float_as_uint(a),__float_as_uint(a),false,false); a=__uint_as_float(rr[0])+__uint_as_float(rr[1]); }
;       g[n]=(n<qb)?a:-INFINITY; }
	v_and_b32_e32 v1, 32, v17
	v_add_u32_e32 v1, 0, v1
	v_add_u32_e32 v1, 0x14800, v1
	ds_read_b128 v[2:5], v1
	ds_read_b128 v[6:9], v1 offset:16
	s_waitcnt vmcnt(3)
	v_cvt_f32_f16_e32 v30, v144
	v_cvt_f32_f16_sdwa v31, v144 dst_sel:DWORD dst_unused:UNUSED_PAD src0_sel:WORD_1
	v_cvt_f32_f16_e32 v32, v145
	s_waitcnt lgkmcnt(1)
	v_fma_mix_f32 v2, v2, v144, 0 op_sel_hi:[0,1,0]
	v_fma_mix_f32 v2, v3, v144, v2 op_sel:[0,1,0] op_sel_hi:[0,1,0]
	v_fma_mix_f32 v2, v4, v145, v2 op_sel_hi:[0,1,0]
	v_fma_mix_f32 v2, v5, v145, v2 op_sel:[0,1,0] op_sel_hi:[0,1,0]
	s_waitcnt lgkmcnt(0)
	v_fma_mix_f32 v2, v6, v146, v2 op_sel_hi:[0,1,0]
	v_fma_mix_f32 v2, v7, v146, v2 op_sel:[0,1,0] op_sel_hi:[0,1,0]
	v_fma_mix_f32 v6, v8, v147, v2 op_sel_hi:[0,1,0]
	ds_read_b128 v[2:5], v1 offset:64
	v_fma_mix_f32 v10, v9, v147, v6 op_sel:[0,1,0] op_sel_hi:[0,1,0]
	ds_read_b128 v[6:9], v1 offset:80
	v_cvt_f32_f16_sdwa v33, v145 dst_sel:DWORD dst_unused:UNUSED_PAD src0_sel:WORD_1
	v_cvt_f32_f16_e32 v34, v146
	s_waitcnt lgkmcnt(1)
	v_fma_mix_f32 v2, v2, v148, v10 op_sel_hi:[0,1,0]
	v_fma_mix_f32 v2, v3, v148, v2 op_sel:[0,1,0] op_sel_hi:[0,1,0]
	v_fma_mix_f32 v2, v4, v149, v2 op_sel_hi:[0,1,0]
	v_fma_mix_f32 v2, v5, v149, v2 op_sel:[0,1,0] op_sel_hi:[0,1,0]
	s_waitcnt lgkmcnt(0)
	v_fma_mix_f32 v2, v6, v150, v2 op_sel_hi:[0,1,0]
	v_fma_mix_f32 v2, v7, v150, v2 op_sel:[0,1,0] op_sel_hi:[0,1,0]
	v_fma_mix_f32 v6, v8, v151, v2 op_sel_hi:[0,1,0]
	ds_read_b128 v[2:5], v1 offset:128
	ds_read_b128 v[10:13], v1 offset:144
	v_fma_mix_f32 v6, v9, v151, v6 op_sel:[0,1,0] op_sel_hi:[0,1,0]
	v_cvt_f32_f16_sdwa v35, v146 dst_sel:DWORD dst_unused:UNUSED_PAD src0_sel:WORD_1
	v_cvt_f32_f16_e32 v36, v147
	s_waitcnt lgkmcnt(1)
	v_fma_mix_f32 v2, v2, v152, v6 op_sel_hi:[0,1,0]
	v_fma_mix_f32 v2, v3, v152, v2 op_sel:[0,1,0] op_sel_hi:[0,1,0]
	v_fma_mix_f32 v2, v4, v153, v2 op_sel_hi:[0,1,0]
	v_fma_mix_f32 v2, v5, v153, v2 op_sel:[0,1,0] op_sel_hi:[0,1,0]
	s_waitcnt lgkmcnt(0)
	v_fma_mix_f32 v2, v10, v154, v2 op_sel_hi:[0,1,0]
	v_fma_mix_f32 v2, v11, v154, v2 op_sel:[0,1,0] op_sel_hi:[0,1,0]
	v_fma_mix_f32 v6, v12, v155, v2 op_sel_hi:[0,1,0]
	ds_read_b128 v[2:5], v1 offset:192
	ds_read_b128 v[38:41], v1 offset:208
	v_fma_mix_f32 v12, v13, v155, v6 op_sel:[0,1,0] op_sel_hi:[0,1,0]
	v_cvt_f32_f16_sdwa v37, v147 dst_sel:DWORD dst_unused:UNUSED_PAD src0_sel:WORD_1
	v_cvt_f32_f16_e32 v26, v148
	s_waitcnt lgkmcnt(1)
	v_fma_mix_f32 v2, v2, v156, v12 op_sel_hi:[0,1,0]
	v_fma_mix_f32 v2, v3, v156, v2 op_sel:[0,1,0] op_sel_hi:[0,1,0]
	v_fma_mix_f32 v2, v4, v157, v2 op_sel_hi:[0,1,0]
	v_fma_mix_f32 v4, v5, v157, v2 op_sel:[0,1,0] op_sel_hi:[0,1,0]
	s_waitcnt lgkmcnt(0)
	v_fma_mix_f32 v4, v38, v158, v4 op_sel_hi:[0,1,0]
	v_fma_mix_f32 v14, v39, v158, v4 op_sel:[0,1,0] op_sel_hi:[0,1,0]
	v_cvt_f32_f16_sdwa v27, v148 dst_sel:DWORD dst_unused:UNUSED_PAD src0_sel:WORD_1
	v_cvt_f32_f16_e32 v28, v149
	v_cvt_f32_f16_sdwa v29, v149 dst_sel:DWORD dst_unused:UNUSED_PAD src0_sel:WORD_1
	v_cvt_f32_f16_e32 v22, v150
	v_cvt_f32_f16_sdwa v23, v150 dst_sel:DWORD dst_unused:UNUSED_PAD src0_sel:WORD_1
	v_cvt_f32_f16_e32 v24, v151
	v_cvt_f32_f16_sdwa v25, v151 dst_sel:DWORD dst_unused:UNUSED_PAD src0_sel:WORD_1
	v_cvt_f32_f16_e32 v18, v152
	v_cvt_f32_f16_sdwa v19, v152 dst_sel:DWORD dst_unused:UNUSED_PAD src0_sel:WORD_1
	v_cvt_f32_f16_e32 v20, v153
	v_cvt_f32_f16_sdwa v21, v153 dst_sel:DWORD dst_unused:UNUSED_PAD src0_sel:WORD_1
	v_cvt_f32_f16_sdwa v9, v154 dst_sel:DWORD dst_unused:UNUSED_PAD src0_sel:WORD_1
	v_cvt_f32_f16_e32 v8, v154
	v_cvt_f32_f16_sdwa v11, v155 dst_sel:DWORD dst_unused:UNUSED_PAD src0_sel:WORD_1
	v_cvt_f32_f16_e32 v10, v155
	v_cvt_f32_f16_sdwa v7, v156 dst_sel:DWORD dst_unused:UNUSED_PAD src0_sel:WORD_1
	v_cvt_f32_f16_e32 v6, v156
	v_cvt_f32_f16_sdwa v13, v157 dst_sel:DWORD dst_unused:UNUSED_PAD src0_sel:WORD_1
	v_cvt_f32_f16_e32 v12, v157
	v_cvt_f32_f16_sdwa v3, v158 dst_sel:DWORD dst_unused:UNUSED_PAD src0_sel:WORD_1
	v_cvt_f32_f16_e32 v2, v158
	v_cvt_f32_f16_sdwa v5, v159 dst_sel:DWORD dst_unused:UNUSED_PAD src0_sel:WORD_1
	v_cvt_f32_f16_e32 v4, v159
	v_fma_mix_f32 v14, v40, v159, v14 op_sel_hi:[0,1,0]
	v_fma_mix_f32 v14, v41, v159, v14 op_sel:[0,1,0] op_sel_hi:[0,1,0]
	v_mov_b32_e32 v15, v14
	s_nop 1
	v_permlane32_swap_b32_e32 v14, v15
	v_mov_b32_e32 v38, 0
	s_cmp_eq_u32 s20, 1
	v_mov_b32_e32 v39, 0
	s_cbranch_scc1 .LBB0_450
	ds_read_b128 v[40:43], v1 offset:256
	ds_read_b128 v[44:47], v1 offset:272
	s_waitcnt lgkmcnt(1)
	v_fma_f32 v39, v40, v30, 0
	v_fmac_f32_e32 v39, v41, v31
	v_fmac_f32_e32 v39, v42, v32
	v_fmac_f32_e32 v39, v43, v33
	ds_read_b128 v[40:43], v1 offset:320
	s_waitcnt lgkmcnt(1)
	v_fmac_f32_e32 v39, v44, v34
	v_fmac_f32_e32 v39, v45, v35
	v_fmac_f32_e32 v39, v46, v36
	v_fmac_f32_e32 v39, v47, v37
	s_waitcnt lgkmcnt(0)
	v_fmac_f32_e32 v39, v40, v26
	v_fmac_f32_e32 v39, v41, v27
	v_fmac_f32_e32 v39, v42, v28
	v_fmac_f32_e32 v39, v43, v29
	ds_read_b128 v[40:43], v1 offset:336
	s_waitcnt lgkmcnt(0)
	v_fmac_f32_e32 v39, v40, v22
	v_fmac_f32_e32 v39, v41, v23
	v_fmac_f32_e32 v39, v42, v24
	v_fmac_f32_e32 v39, v43, v25
	ds_read_b128 v[40:43], v1 offset:384
	s_waitcnt lgkmcnt(0)
	v_fmac_f32_e32 v39, v40, v18
	v_fmac_f32_e32 v39, v41, v19
	v_fmac_f32_e32 v39, v42, v20
	v_fmac_f32_e32 v39, v43, v21
	ds_read_b128 v[40:43], v1 offset:400
	s_waitcnt lgkmcnt(0)
	v_pk_mul_f32 v[40:41], v[40:41], v[8:9]
	s_nop 0
	v_add_f32_e32 v39, v39, v40
	v_add_f32_e32 v39, v39, v41
	v_pk_mul_f32 v[40:41], v[42:43], v[10:11]
	s_nop 0
	v_add_f32_e32 v39, v39, v40
	v_add_f32_e32 v39, v39, v41
	ds_read_b128 v[40:43], v1 offset:448
	s_waitcnt lgkmcnt(0)
	v_pk_mul_f32 v[40:41], v[40:41], v[6:7]
	s_nop 0
	v_add_f32_e32 v39, v39, v40
	v_add_f32_e32 v39, v39, v41
	v_pk_mul_f32 v[40:41], v[42:43], v[12:13]
	s_nop 0
	v_add_f32_e32 v39, v39, v40
	v_add_f32_e32 v39, v39, v41
	ds_read_b128 v[40:43], v1 offset:464
	s_waitcnt lgkmcnt(0)
	v_pk_mul_f32 v[40:41], v[40:41], v[2:3]
	s_nop 0
	v_add_f32_e32 v39, v39, v40
	v_add_f32_e32 v39, v39, v41
	v_pk_mul_f32 v[40:41], v[42:43], v[4:5]
	s_nop 0
	v_add_f32_e32 v39, v39, v40
	v_add_f32_e32 v39, v39, v41

; __device__ __forceinline__ void qkt(f32x16&p0,f32x16&p1,const char*Kslot,const bf16x8*qr,const f32x16&negm,int r32,int hi){
;   const char*kb=Kslot+hi*1024+r32*16;
;   #pragma unroll
;   for(int d0=0;d0<4;++d0){
;     const bf16x8 b0=*reinterpret_cast<const bf16x8*>(kb+d0*2048);
;     const bf16x8 b1=*reinterpret_cast<const bf16x8*>(kb+d0*2048+512);
;     if(d0==0){p0=MF16(b0,qr[0],negm,0,0,0);p1=MF16(b1,qr[0],negm,0,0,0);}
;     else{p0=MF16(b0,qr[d0],p0,0,0,0);p1=MF16(b1,qr[d0],p1,0,0,0);}}
; }
; __device__ __forceinline__ void kload8(bf16x8*kf,lds_cptr kp){
;   kf[0]=*(const __attribute__((address_space(3))) bf16x8*)(kp);      kf[1]=*(const __attribute__((address_space(3))) bf16x8*)(kp+512);
;   kf[2]=*(const __attribute__((address_space(3))) bf16x8*)(kp+2048); kf[3]=*(const __attribute__((address_space(3))) bf16x8*)(kp+2560);
;   kf[4]=*(const __attribute__((address_space(3))) bf16x8*)(kp+4096); kf[5]=*(const __attribute__((address_space(3))) bf16x8*)(kp+4608);
;   kf[6]=*(const __attribute__((address_space(3))) bf16x8*)(kp+6144); kf[7]=*(const __attribute__((address_space(3))) bf16x8*)(kp+6656);
; }
; __device__ __forceinline__ void kload2(bf16x8*kf,lds_cptr kp,int j){ kf[2*j]=*(const __attribute__((address_space(3))) bf16x8*)(kp+j*2048); kf[2*j+1]=*(const __attribute__((address_space(3))) bf16x8*)(kp+j*2048+512); }
; __device__ __forceinline__ s16x4 vtr(lds_cptr p){ return __builtin_bit_cast(s16x4,__builtin_amdgcn_ds_read_tr16_b64_v4i16((__attribute__((address_space(3))) v4i16_t*)p)); }
; __device__ __forceinline__ float rowmax(const f32x16&p0,const f32x16&p1){
; template<int THRL> __device__ __forceinline__ void attn_unit(int b,int h,int qb,const bf16*Q,const bf16*__restrict__ K,const bf16*__restrict__ V,bf16*O,char*shm,const float*KMg,const float*rel_bias,bool newhead,bf16x8 (&qr)[4],const bf16*Qnext){
;     ...
;   float mhat=0.f,l_reg=0.f;f32x16 o[2];o[0]=f32x16{};o[1]=f32x16{};f32x16 negm=f32x16{};asm volatile("":"+v"(negm));
;   const int qrel=wid*QBLK+r32;
;     ...
;   bool resc=false;
;     ...
;   f32x16 pA0,pA1,pB0,pB1;
;   int sl_prev=0,sl_cur=0,sl_next=SLOTB;
;     ...
;   DMA_K(2,2*SLOTB);
;   WAIT_BAR(3);
;   qkt(pA0,pA1,Kbase,qr,negm,r32,hi);asm volatile("s_nop 15\n\ts_nop 7":"+v"(pA0),"+v"(pA1));CMASK(pA0,pA1,0);
;   START(pA0,pA1);
;   _Pragma("unroll") for(int r=0;r<16;++r)pA1[r]=__builtin_amdgcn_exp2f(pA1[r]);
;   WAIT_BAR(0);
.LBB0_466:
	s_add_i32 s58, s28, -2
	s_lshl_b32 s71, s77, 5
	s_lshl_b64 s[16:17], s[58:59], 13
	v_mov_b32_e32 v14, v0
	s_waitcnt vmcnt(3)
	v_mov_b32_e32 v15, v0
	s_cmp_lg_u32 0, -1
	v_add3_u32 v245, 0, v1, v2
	v_mov_b32_e32 v1, v0
	v_mov_b32_e32 v2, v0
	v_mov_b32_e32 v3, v0
	v_mov_b32_e32 v4, v0
	v_mov_b32_e32 v5, v0
	v_mov_b32_e32 v6, v0
	v_mov_b32_e32 v7, v0
	v_mov_b32_e32 v8, v0
	v_mov_b32_e32 v9, v0
	v_mov_b32_e32 v10, v0
	v_mov_b32_e32 v11, v0
	v_mov_b32_e32 v12, v0
	v_mov_b32_e32 v13, v0
	v_mov_b64_e32 v[32:33], v[14:15]
	s_cselect_b32 s12, 0, 0
	v_mov_b64_e32 v[30:31], v[12:13]
	v_mov_b64_e32 v[28:29], v[10:11]
	v_mov_b64_e32 v[26:27], v[8:9]
	v_mov_b64_e32 v[24:25], v[6:7]
	v_mov_b64_e32 v[22:23], v[4:5]
	v_mov_b64_e32 v[20:21], v[2:3]
	v_mov_b64_e32 v[18:19], v[0:1]
	s_add_i32 s12, s12, s24
	v_lshl_add_u64 v[2:3], v[218:219], 0, s[16:17]
	s_add_i32 s13, s12, 0x4000
	s_mov_b32 s20, m0
	s_mov_b32 m0, s13
	s_nop 0
	global_load_lds_dwordx4 v[2:3], off
	s_mov_b32 m0, s20
	s_waitcnt vmcnt(3) lgkmcnt(0)
	s_barrier
	ds_read_b128 v[2:5], v245
	ds_read_b128 v[6:9], v245 offset:512
	s_waitcnt lgkmcnt(1)
	v_mfma_f32_32x32x16_f16 v[34:49], v[2:5], v[144:147], v[18:33]
	v_lshlrev_b32_e32 v1, 1, v17
	v_lshlrev_b32_e32 v140, 2, v241
	v_and_b32_e32 v1, 32, v1
	s_lshl_b32 s13, s82, 6
	v_or_b32_e32 v14, s71, v242
	s_addk_i32 s13, 0x17f
	s_add_i32 s26, s28, -1
	s_waitcnt lgkmcnt(0)
	v_mfma_f32_32x32x16_f16 v[18:33], v[6:9], v[144:147], v[18:33]
	ds_read_b128 v[2:5], v245 offset:2048
	ds_read_b128 v[6:9], v245 offset:2560
	s_mov_b32 s27, s59
	s_lshl_b64 s[26:27], s[26:27], 13
	s_add_i32 s12, s12, 0x8000
	v_mov_b64_e32 v[234:235], 0x400
	s_waitcnt lgkmcnt(1)
	v_mfma_f32_32x32x16_f16 v[34:49], v[2:5], v[148:151], v[34:49]
	s_waitcnt lgkmcnt(0)
	v_mfma_f32_32x32x16_f16 v[18:33], v[6:9], v[148:151], v[18:33]
	ds_read_b128 v[2:5], v245 offset:4096
	ds_read_b128 v[6:9], v245 offset:4608
	s_waitcnt lgkmcnt(1)
	v_mfma_f32_32x32x16_f16 v[34:49], v[2:5], v[152:155], v[34:49]
	s_waitcnt lgkmcnt(0)
	v_mfma_f32_32x32x16_f16 v[18:33], v[6:9], v[152:155], v[18:33]
	ds_read_b128 v[2:5], v245 offset:6144
	ds_read_b128 v[6:9], v245 offset:6656
	s_waitcnt lgkmcnt(1)
	v_mfma_f32_32x32x16_f16 v[34:49], v[2:5], v[156:159], v[34:49]
	v_lshrrev_b32_e32 v2, 2, v17
	v_and_or_b32 v2, v2, 3, v140
	v_lshlrev_b32_e32 v243, 6, v2
	v_add_u32_e32 v2, 0, v1
	v_add3_u32 v246, v2, v240, v243
	v_add_u32_e32 v17, s5, v14
	v_add_u32_e32 v2, s13, v140
	v_sub_u32_e32 v2, v2, v17
	v_and_b32_e32 v3, 3, v2
	v_lshlrev_b32_e32 v2, 2, v2
	v_mul_u32_u24_e32 v3, 0xa00, v3
	v_and_b32_e32 v2, -16, v2
	v_readlane_b32 s13, v255, 24
	s_waitcnt lgkmcnt(0)
	v_mfma_f32_32x32x16_f16 v[18:33], v[6:9], v[156:159], v[18:33]
	s_nop 15
	s_nop 7
	v_add3_u32 v15, s13, v3, v2
	ds_read_b128 v[2:5], v15
	ds_read_b128 v[6:9], v15 offset:32
	ds_read_b128 v[10:13], v15 offset:128
	ds_read_b128 v[50:53], v15 offset:160
	ds_read_b128 v[54:57], v15 offset:64
	ds_read_b128 v[58:61], v15 offset:96
	ds_read_b128 v[62:65], v15 offset:192
	ds_read_b128 v[66:69], v15 offset:224
	s_waitcnt lgkmcnt(7)
	v_add_f32_e32 v2, v34, v2
	s_waitcnt lgkmcnt(5)
	v_add_f32_e32 v10, v18, v10
	v_add_f32_e32 v3, v35, v3
	v_max3_f32 v15, v2, v3, v10
	v_add_f32_e32 v11, v19, v11
	v_add_f32_e32 v4, v36, v4
	v_add_f32_e32 v12, v20, v12
	v_add_f32_e32 v5, v37, v5
	v_add_f32_e32 v13, v21, v13
	v_add_f32_e32 v6, v38, v6
	v_max3_f32 v38, v4, v5, v11
	v_max3_f32 v15, v15, v12, v13
	v_add_f32_e32 v7, v39, v7
	v_add_f32_e32 v8, v40, v8
	v_add_f32_e32 v9, v41, v9
	v_max3_f32 v15, v15, v6, v7
	v_max3_f32 v38, v38, v8, v9
	s_waitcnt lgkmcnt(4)
	v_add_f32_e32 v18, v22, v50
	v_add_f32_e32 v19, v23, v51
	v_add_f32_e32 v20, v24, v52
	v_add_f32_e32 v21, v25, v53
	v_max3_f32 v15, v15, v18, v19
	v_max3_f32 v38, v38, v20, v21
	s_waitcnt lgkmcnt(3)
	v_add_f32_e32 v22, v42, v54
	s_waitcnt lgkmcnt(1)
	v_add_f32_e32 v23, v26, v62
	v_add_f32_e32 v24, v43, v55
	v_add_f32_e32 v25, v27, v63
	v_add_f32_e32 v26, v44, v56
	v_add_f32_e32 v27, v28, v64
	v_add_f32_e32 v28, v45, v57
	v_max3_f32 v15, v15, v22, v24
	v_max3_f32 v38, v38, v26, v28
	v_add_f32_e32 v29, v29, v65
	v_max3_f32 v15, v15, v23, v25
	v_max3_f32 v38, v38, v27, v29
	v_add_f32_e32 v34, v46, v58
	v_add_f32_e32 v35, v47, v59
	v_add_f32_e32 v36, v48, v60
	v_add_f32_e32 v37, v49, v61
	v_max3_f32 v15, v15, v34, v35
	v_max3_f32 v38, v38, v36, v37
	s_waitcnt lgkmcnt(0)
	v_add_f32_e32 v30, v30, v66
	v_add_f32_e32 v31, v31, v67
	v_add_f32_e32 v32, v32, v68
	v_add_f32_e32 v33, v33, v69
	v_max3_f32 v15, v15, v30, v31
	v_max3_f32 v38, v38, v32, v33
	s_nop 0
	v_max_f32_e32 v15, v15, v38
	s_nop 0
	v_mov_b32_e32 v38, v15
	s_nop 1
	v_permlane32_swap_b32_e32 v15, v38
	v_max_f32_e32 v38, v15, v38
	s_nop 0
	v_add_f32_e32 v15, v0, v38
	v_sub_f32_e32 v39, v2, v38
	v_sub_f32_e32 v41, v3, v38
	v_lshl_add_u64 v[2:3], v[218:219], 0, s[26:27]
	v_xor_b32_e32 v64, 0x80000000, v15
	v_mov_b32_e32 v65, v64
	v_mov_b32_e32 v66, v64
	v_mov_b32_e32 v67, v64
	v_mov_b32_e32 v68, v64
	v_mov_b32_e32 v69, v64
	v_mov_b32_e32 v70, v64
	v_mov_b32_e32 v71, v64
	v_mov_b32_e32 v72, v64
	v_mov_b32_e32 v73, v64
	v_mov_b32_e32 v74, v64
	v_mov_b32_e32 v75, v64
	v_mov_b32_e32 v76, v64
	v_mov_b32_e32 v77, v64
	v_mov_b32_e32 v78, v64
	v_mov_b32_e32 v79, v64
	s_waitcnt vmcnt(0) lgkmcnt(0)
	s_barrier
; #define WAIT_BAR(N) asm volatile("s_waitcnt vmcnt(" #N ") lgkmcnt(0)\n\ts_barrier":::"memory")
;   #define DMA_K(t,slot) glds16(ksrc+(long)(TKT(t))*KVBLK*D,(unsigned)__builtin_amdgcn_readfirstlane(kdst+(slot)))
;   #define DMA_V(t,slot) glds16(vsrc+(long)(TKT(t))*KVBLK*D,(unsigned)__builtin_amdgcn_readfirstlane(vdst+(slot)))
;   #define ROT() do{sl_prev=sl_cur;sl_cur=sl_next;sl_next=(sl_next==(NSLOT-1)*SLOTB)?0:sl_next+SLOTB;}while(0)
; template<int THRL> __device__ __forceinline__ void attn_unit(int b,int h,int qb,const bf16*Q,const bf16*__restrict__ K,const bf16*__restrict__ V,bf16*O,char*shm,const float*KMg,const float*rel_bias,bool newhead,bf16x8 (&qr)[4],const bf16*Qnext){
;     ...
;   WAIT_BAR(0);
;   DMA_K(3,0);DMA_V(1,SLOTB);
;   ROT();
;   kload8(kf,kp0+sl_cur);
;   WAIT_BAR(2);
;   s16x4 vlo[8],vhi[8]; u32x4 pw0,pw1,pw2,pw3;
	s_mov_b32 s13, m0
	s_mov_b32 m0, s33
	s_nop 0
	global_load_lds_dwordx4 v[2:3], off
	s_mov_b32 m0, s13
	v_lshl_add_u64 v[2:3], s[22:23], 1, v[220:221]
	s_mov_b32 s13, m0
	s_mov_b32 m0, s12
	s_nop 0
	global_load_lds_dwordx4 v[2:3], off
	s_mov_b32 m0, s13
	v_sub_f32_e32 v40, v10, v38
	v_sub_f32_e32 v42, v11, v38
	v_sub_f32_e32 v43, v4, v38
	v_sub_f32_e32 v44, v12, v38
	v_sub_f32_e32 v45, v5, v38
	v_sub_f32_e32 v46, v13, v38
	ds_read_b128 v[2:5], v245 offset:8192
	ds_read_b128 v[10:13], v245 offset:8704
	ds_read_b128 v[58:61], v245 offset:10240
	ds_read_b128 v[84:87], v245 offset:10752
	ds_read_b128 v[88:91], v245 offset:12288
	ds_read_b128 v[92:95], v245 offset:12800
	ds_read_b128 v[96:99], v245 offset:14336
	ds_read_b128 v[100:103], v245 offset:14848
	v_sub_f32_e32 v37, v37, v38
	v_sub_f32_e32 v6, v6, v38
	v_sub_f32_e32 v18, v18, v38
	v_sub_f32_e32 v7, v7, v38
	v_sub_f32_e32 v19, v19, v38
	v_sub_f32_e32 v8, v8, v38
	v_sub_f32_e32 v20, v20, v38
	v_sub_f32_e32 v9, v9, v38
	v_sub_f32_e32 v21, v21, v38
	v_sub_f32_e32 v22, v22, v38
	v_sub_f32_e32 v23, v23, v38
	v_sub_f32_e32 v24, v24, v38
	v_sub_f32_e32 v25, v25, v38
	v_sub_f32_e32 v26, v26, v38
	v_sub_f32_e32 v27, v27, v38
	v_sub_f32_e32 v28, v28, v38
	v_sub_f32_e32 v29, v29, v38
	v_sub_f32_e32 v34, v34, v38
	v_sub_f32_e32 v30, v30, v38
	v_sub_f32_e32 v35, v35, v38
	v_sub_f32_e32 v31, v31, v38
	v_sub_f32_e32 v36, v36, v38
	v_sub_f32_e32 v32, v32, v38
	v_sub_f32_e32 v33, v33, v38
	s_nop 0
	v_exp_f32_e32 v62, v37
	v_exp_f32_e32 v37, v39
	v_exp_f32_e32 v38, v41
	v_exp_f32_e32 v39, v43
	v_exp_f32_e32 v41, v45
	v_exp_f32_e32 v43, v6
	v_exp_f32_e32 v45, v7
	v_exp_f32_e32 v80, v9
	v_exp_f32_e32 v112, v40
	v_exp_f32_e32 v113, v42
	v_exp_f32_e32 v114, v44
	v_exp_f32_e32 v115, v46
	v_exp_f32_e32 v116, v18
	v_exp_f32_e32 v117, v19
	v_exp_f32_e32 v118, v20
	v_exp_f32_e32 v119, v21
	v_exp_f32_e32 v120, v23
	v_exp_f32_e32 v121, v25
	v_exp_f32_e32 v122, v27
	v_exp_f32_e32 v123, v29
	s_waitcnt vmcnt(2) lgkmcnt(0)
	s_barrier
	v_exp_f32_e32 v63, v8
	v_exp_f32_e32 v104, v22
	v_exp_f32_e32 v105, v24
	v_exp_f32_e32 v106, v26
	v_exp_f32_e32 v107, v28
	v_exp_f32_e32 v108, v34
	v_exp_f32_e32 v109, v35
	v_exp_f32_e32 v110, v36
	v_exp_f32_e32 v111, v33
	v_exp_f32_e32 v132, v30
	v_exp_f32_e32 v133, v31
	v_exp_f32_e32 v134, v32
	ds_read_b64_tr_b16 v[54:55], v246 offset:24576
	ds_read_b64_tr_b16 v[56:57], v246 offset:25088
	s_waitcnt lgkmcnt(9)
	v_mfma_f32_32x32x16_f16 v[18:33], v[2:5], v[144:147], v[64:79]
	v_add_f32_e32 v6, v37, v38
	v_add_f32_e32 v6, v6, v39
	v_add_f32_e32 v6, v6, v41
	v_add_f32_e32 v6, v6, v43
	v_add_f32_e32 v34, v6, v45
	v_cvt_pk_f16_f32 v6, v37, v38
	v_cvt_pk_f16_f32 v7, v39, v41
	ds_read_b64_tr_b16 v[50:51], v246 offset:28672
	ds_read_b64_tr_b16 v[52:53], v246 offset:29184
	v_add_f32_e32 v2, v63, v34
	v_cvt_pk_f16_f32 v8, v43, v45
	s_waitcnt lgkmcnt(10)
	v_mfma_f32_32x32x16_f16 v[34:49], v[10:13], v[144:147], v[64:79]
	v_add_f32_e32 v2, v80, v2
	v_add_f32_e32 v2, v104, v2
	v_add_f32_e32 v2, v105, v2
	v_cvt_pk_f16_f32 v9, v63, v80
	ds_read_b64_tr_b16 v[80:81], v246 offset:25600
	ds_read_b64_tr_b16 v[82:83], v246 offset:26112
	s_waitcnt lgkmcnt(11)
	v_mfma_f32_32x32x16_f16 v[18:33], v[58:61], v[148:151], v[18:33]
	v_add_f32_e32 v2, v106, v2
	v_add_f32_e32 v2, v107, v2
	v_add_f32_e32 v2, v108, v2
	v_add_f32_e32 v10, v109, v2
	v_cvt_pk_f16_f32 v2, v104, v105
	v_cvt_pk_f16_f32 v3, v106, v107
	ds_read_b64_tr_b16 v[124:125], v246 offset:29696
	ds_read_b64_tr_b16 v[126:127], v246 offset:30208
	s_waitcnt lgkmcnt(12)
	v_mfma_f32_32x32x16_f16 v[34:49], v[84:87], v[148:151], v[34:49]
	v_add_f32_e32 v4, v110, v10
	v_add_f32_e32 v4, v62, v4
	v_add_f32_e32 v4, v112, v4
	v_add_f32_e32 v10, v113, v4
	v_cvt_pk_f16_f32 v4, v108, v109
	v_cvt_pk_f16_f32 v5, v110, v62
	ds_read_b64_tr_b16 v[128:129], v246 offset:26624
	ds_read_b64_tr_b16 v[130:131], v246 offset:27136
	s_waitcnt lgkmcnt(13)
	v_mfma_f32_32x32x16_f16 v[18:33], v[88:91], v[152:155], v[18:33]
	v_add_f32_e32 v10, v114, v10
	v_add_f32_e32 v10, v115, v10
	v_add_f32_e32 v10, v116, v10
	v_add_f32_e32 v58, v117, v10
	v_cvt_pk_f16_f32 v10, v112, v113
	v_cvt_pk_f16_f32 v11, v114, v115
	ds_read_b64_tr_b16 v[112:113], v246 offset:30720
	ds_read_b64_tr_b16 v[114:115], v246 offset:31232
	s_waitcnt lgkmcnt(14)
	v_mfma_f32_32x32x16_f16 v[34:49], v[92:95], v[152:155], v[34:49]
	v_add_f32_e32 v12, v118, v58
	v_add_f32_e32 v12, v119, v12
	v_add_f32_e32 v12, v120, v12
	v_add_f32_e32 v58, v121, v12
	v_cvt_pk_f16_f32 v12, v116, v117
	v_cvt_pk_f16_f32 v13, v118, v119
	ds_read_b64_tr_b16 v[116:117], v246 offset:27648
	ds_read_b64_tr_b16 v[118:119], v246 offset:28160
	s_waitcnt lgkmcnt(14)
	v_mfma_f32_32x32x16_f16 v[18:33], v[96:99], v[156:159], v[18:33]
	v_add_f32_e32 v58, v122, v58
	v_add_f32_e32 v58, v123, v58
	v_add_f32_e32 v58, v132, v58
	v_add_f32_e32 v58, v133, v58
	v_cvt_pk_f16_f32 v160, v120, v121
	v_cvt_pk_f16_f32 v161, v122, v123
	ds_read_b64_tr_b16 v[120:121], v246 offset:31744
	ds_read_b64_tr_b16 v[122:123], v246 offset:32256
	v_mfma_f32_32x32x16_f16 v[34:49], v[100:103], v[156:159], v[34:49]
	v_add_f32_e32 v58, v134, v58
	v_add_f32_e32 v58, v111, v58
	v_add_f32_e32 v58, 0, v58
	v_cvt_pk_f16_f32 v162, v132, v133
	v_cvt_pk_f16_f32 v163, v134, v111
	v_cndmask_b32_e64 v59, 0, 1, s[8:9]
	v_cmp_ne_u32_e64 s[38:39], 1, v59
	s_andn2_b64 vcc, exec, s[8:9]
	s_cbranch_vccnz .LBB0_468
	s_lshl_b32 s22, s28, 13
	s_mov_b32 s23, s59
	s_cmp_lg_u32 0, -1
	v_lshl_add_u64 v[60:61], v[218:219], 0, s[22:23]
	s_mov_b32 s22, 0xffff6000
	s_cselect_b32 s12, 0, 0
	s_mov_b32 s23, -1
	s_add_i32 s12, s12, s24
	v_lshl_add_u64 v[60:61], v[60:61], 0, s[22:23]
	s_addk_i32 s12, 0x2000
	s_mov_b32 s13, m0
	s_mov_b32 m0, s12
	s_nop 0
	global_load_lds_dwordx4 v[60:61], off
	s_mov_b32 m0, s13
